# adaLN modulation units: each wave prefetches its 128x256B slice of w_ada (4 line-granular loads into unused registers) at unit start so the 8 dependent load/FMA rounds hit L2; stacked on stack24
# baseline (speedup 1.0000x reference)
; #define LAS __attribute__((address_space(3)))
; __device__ __forceinline__ const float* arg_in(int k) { const int o = launder_s(k * 8); return *(const float* const*)((const char*)__builtin_amdgcn_kernarg_segment_ptr() + o); }
; __device__ __forceinline__ void p0_mod_unit(const float* __restrict__ c, const float* __restrict__ w_ada, const float* __restrict__ b_ada, float* __restrict__ mod, int unit, LAS float* lds, int tid) {
;     LAS float* sc = lds;
;     LAS float* red = lds + 8192;
;     const int l = unit / 96, j0 = (unit % 96) * 64, col = tid & 63, kq = tid >> 6;
;     for (int i = tid; i < 8192; i += NTHR) { const float v = c[i]; sc[i] = v / (1.f + __expf(-v)); }
;     __syncthreads();
;     float acc[8] = {0.f, 0.f, 0.f, 0.f, 0.f, 0.f, 0.f, 0.f};
;     const float* w = w_ada + (size_t)l * 1024 * 6144 + j0 + col;
;     for (int k = kq * 128; k < kq * 128 + 128; k += 16) { float wv[16];
; #pragma unroll
;         for (int j = 0; j < 16; ++j) wv[j] = w[(size_t)(k + j) * 6144];
; __global__ void __launch_bounds__(NTHR, 2) mk_fwd(Args a) {
;     ...
;         for (int u = bx; u < 192; u += G) p0_mod_unit(arg_in(1), arg_in(2), arg_in(3), mod, u, (LAS float*)ldsl, tid);
.LBB0_35:
	s_mov_b32 s4, 8
	s_ashr_i32 s5, s4, 31
	s_add_u32 s4, s0, s4
	s_addc_u32 s5, s1, s5
	s_load_dwordx2 s[18:19], s[4:5], 0x0
	s_mov_b32 s4, 16
	s_ashr_i32 s5, s4, 31
	s_add_u32 s4, s0, s4
	s_addc_u32 s5, s1, s5
	s_mov_b32 s14, 24
	s_load_dwordx2 s[4:5], s[4:5], 0x0
	s_ashr_i32 s15, s14, 31
	s_add_u32 s14, s0, s14
	s_addc_u32 s15, s1, s15
	s_load_dwordx2 s[16:17], s[14:15], 0x0
	s_movk_i32 s14, 0xa0
	s_ashr_i32 s15, s14, 31
	s_add_u32 s14, s0, s14
	s_addc_u32 s15, s1, s15
	s_load_dwordx2 s[14:15], s[14:15], 0x0
	s_waitcnt lgkmcnt(0)
	s_mul_hi_i32 vcc_lo, s29, 0x2aaaaaab
	s_lshr_b32 vcc_hi, vcc_lo, 31
	s_ashr_i32 vcc_lo, vcc_lo, 4
	s_add_i32 vcc_lo, vcc_lo, vcc_hi
	s_mul_i32 vcc_hi, vcc_lo, 0x60
	s_sub_i32 vcc_hi, s29, vcc_hi
	s_lshl_b32 vcc_hi, vcc_hi, 8
	s_mul_i32 s98, vcc_lo, 0x1800000
	s_add_u32 s98, s98, vcc_hi
	s_add_u32 s98, s4, s98
	s_addc_u32 s99, s5, 0
	v_lshrrev_b32_e32 v180, 6, v212
	v_and_b32_e32 v181, 63, v212
	v_lshrrev_b32_e32 v182, 1, v181
	v_lshl_add_u32 v182, v180, 7, v182
	v_mul_u32_u24_e32 v182, 0x6000, v182
	v_and_b32_e32 v181, 1, v181
	v_lshl_add_u32 v182, v181, 7, v182
	v_add_u32_e32 v183, 0xc0000, v182
	v_add_u32_e32 v186, 0x180000, v182
	v_add_u32_e32 v187, 0x240000, v182
	global_load_dword v184, v182, s[98:99]
	global_load_dword v185, v183, s[98:99]
	global_load_dword v188, v186, s[98:99]
	global_load_dword v189, v187, s[98:99]
	v_lshl_add_u64 v[2:3], s[18:19], 0, v[136:137]
	s_mov_b64 s[18:19], 0
	v_mov_b32_e32 v4, v155
	v_mov_b32_e32 v5, v154
